# both K-loop peels plus 64-byte alignment of the three GEMM K-loop heads
# speedup vs baseline: 1.0005x; 1.0005x over previous
; #define PG8_STAGE(bufoff, gbase, voff) do { _Pragma("unroll") for (int _i = 0; _i < 2; ++_i) \
;         __builtin_amdgcn_global_load_lds((const unsigned*)((const char*)(gbase) + (voff)[_i]), (PG8_LAS unsigned*)(lds + (bufoff) + ldsw + _i * 8192), 16, 0, 0); } while (0)
; #define PG8_LDA(dst, b, h) do { _Pragma("unroll") for (int m = 0; m < 4; ++m) _Pragma("unroll") for (int k = 0; k < 2; ++k) dst[m][k] = *(const PG8_LAS bf16x8*)(lds + PG8_SA(b, h) + aoff + m * 2048 + k * 1024); } while (0)
; #define PG8_LDB(dst, b, h) do { _Pragma("unroll") for (int n = 0; n < 2; ++n) _Pragma("unroll") for (int k = 0; k < 2; ++k) dst[n][k] = *(const PG8_LAS bf16x8*)(lds + PG8_SB(b, h) + boff + n * 2048 + k * 1024); } while (0)
; #define PG8_MMA(ai, bj, At, Bt) do { __builtin_amdgcn_s_setprio(1); _Pragma("unroll") for (int m = 0; m < 4; ++m) _Pragma("unroll") for (int n = 0; n < 2; ++n) _Pragma("unroll") for (int k = 0; k < 2; ++k) \
;         acc[ai][bj][m][n] = __builtin_amdgcn_mfma_f32_16x16x32_bf16(Bt[n][k], At[m][k], acc[ai][bj][m][n], 0, 0, 0); __builtin_amdgcn_s_setprio(0); } while (0)
; #define PG8_BAR __builtin_amdgcn_s_barrier()
; template <class Epi, class Sched>
; __device__ __forceinline__ void gemm_phase(PG8_LAS unsigned char* lds, const Gemm g, const Sched& S, const Epi& E) {
;     ...
;         const bool has_next = S.next(ui + 1, nxt);
;         const char* nA = has_next ? (const char*)g.A + (size_t)nxt.pm * tstep : cA; const char* nB = has_next ? (const char*)g.Bt + (size_t)nxt.pn * tstep : cB;
;         for (int t = 0; t < nt; t += 2) {
;             const bool last = (t == nt - 2);
;             const char* a1 = cA + (size_t)(t + 1) * kstep;
;             const char* a2 = last ? nA : cA + (size_t)(t + 2) * kstep; const char* b2 = last ? nB : cB + (size_t)(t + 2) * kstep;
;             const char* a3 = a2 + kstep; const char* b3 = b2 + kstep;
;             PG8_LDB(B0, 0, 0); PG8_LDB(B1, 0, 1); PG8_SCHED; PG8_LDA(At, 0, 0); PG8_STAGE(PG8_SA(1, 1), a1 + hstep, voffA);
;             PG8_WAIT_V(8); PG8_WAIT_L(0); PG8_BAR; PG8_MMA(0, 0, At, B0); PG8_MMA(0, 1, At, B1); PG8_BAR; PG8_SCHED;
;             PG8_LDA(At, 0, 1); PG8_STAGE(PG8_SB(0, 0), b2, voffB); PG8_STAGE(PG8_SB(0, 1), b2 + hstep, voffB); PG8_STAGE(PG8_SA(0, 0), a2, voffA);
;             PG8_WAIT_V(8); PG8_WAIT_L(0); PG8_BAR; PG8_MMA(1, 0, At, B0); PG8_MMA(1, 1, At, B1); PG8_BAR; PG8_SCHED;
.LBB0_317:
	s_add_u32 s42, s42, 0x80
	s_addc_u32 s43, s43, 0
	s_add_u32 s14, s46, 0x100
	s_addc_u32 s15, s47, 0
	s_mov_b32 s34, 0
	s_add_i32 s55, s34, 2
	s_add_u32 s46, s42, 0x80
	s_addc_u32 s47, s43, 0
	s_add_i32 s58, 0, 0x10000
	s_cmp_eq_u32 s39, s34
	s_cselect_b32 s47, s27, s47
	s_cselect_b32 s46, s26, s46
	v_add_u32_e32 v154, s58, v157
	s_cselect_b32 s57, s45, s15
	s_cselect_b32 s56, s44, s14
	s_add_i32 s34, 0, 0x14000
	ds_read_b128 v[130:133], v154
	ds_read_b128 v[146:149], v154 offset:1024
	ds_read_b128 v[150:153], v154 offset:2048
	ds_read_b128 v[160:163], v154 offset:3072
	v_add_u32_e32 v154, s34, v157
	ds_read_b128 v[164:167], v154
	ds_read_b128 v[168:171], v154 offset:1024
	ds_read_b128 v[172:175], v154 offset:2048
	ds_read_b128 v[176:179], v154 offset:3072
	v_lshl_add_u64 v[154:155], s[42:43], 0, v[142:143]
	s_add_i32 m0, s4, 0xc000
	ds_read_b128 v[180:183], v158
	ds_read_b128 v[184:187], v158 offset:1024
	ds_read_b128 v[188:191], v158 offset:2048
	ds_read_b128 v[192:195], v158 offset:3072
	ds_read_b128 v[202:205], v158 offset:4096
	ds_read_b128 v[206:209], v158 offset:5120
	ds_read_b128 v[210:213], v158 offset:6144
	ds_read_b128 v[214:217], v158 offset:7168
	global_load_lds_dwordx4 v[154:155], off
	v_lshl_add_u64 v[154:155], s[42:43], 0, v[144:145]
	s_add_i32 m0, s4, 0xe000
	s_nop 0
	global_load_lds_dwordx4 v[154:155], off
	s_waitcnt vmcnt(8)
	s_waitcnt lgkmcnt(0)
	s_barrier
	s_setprio 1
	s_waitcnt lgkmcnt(0)
	v_mfma_f32_16x16x32_bf16 v[126:129], v[130:133], v[180:183], 0
	v_mfma_f32_16x16x32_bf16 v[118:121], v[150:153], v[180:183], 0
	v_mfma_f32_16x16x32_bf16 v[110:113], v[130:133], v[188:191], 0
	v_mfma_f32_16x16x32_bf16 v[102:105], v[150:153], v[188:191], 0
	v_mfma_f32_16x16x32_bf16 v[94:97], v[130:133], v[202:205], 0
	v_mfma_f32_16x16x32_bf16 v[86:89], v[150:153], v[202:205], 0
	v_mfma_f32_16x16x32_bf16 v[78:81], v[130:133], v[210:213], 0
	v_mfma_f32_16x16x32_bf16 v[70:73], v[150:153], v[210:213], 0
	v_mfma_f32_16x16x32_bf16 v[126:129], v[146:149], v[184:187], v[126:129]
	v_mfma_f32_16x16x32_bf16 v[118:121], v[160:163], v[184:187], v[118:121]
	v_mfma_f32_16x16x32_bf16 v[110:113], v[146:149], v[192:195], v[110:113]
	v_mfma_f32_16x16x32_bf16 v[102:105], v[160:163], v[192:195], v[102:105]
	v_mfma_f32_16x16x32_bf16 v[94:97], v[146:149], v[206:209], v[94:97]
	v_mfma_f32_16x16x32_bf16 v[86:89], v[160:163], v[206:209], v[86:89]
	v_mfma_f32_16x16x32_bf16 v[78:81], v[146:149], v[214:217], v[78:81]
	v_mfma_f32_16x16x32_bf16 v[70:73], v[160:163], v[214:217], v[70:73]
	s_setprio 0
	s_setprio 1
	v_mfma_f32_16x16x32_bf16 v[122:125], v[164:167], v[180:183], 0
	v_mfma_f32_16x16x32_bf16 v[114:117], v[172:175], v[180:183], 0
	v_mfma_f32_16x16x32_bf16 v[106:109], v[164:167], v[188:191], 0
	v_mfma_f32_16x16x32_bf16 v[98:101], v[172:175], v[188:191], 0
	v_mfma_f32_16x16x32_bf16 v[90:93], v[164:167], v[202:205], 0
	v_mfma_f32_16x16x32_bf16 v[82:85], v[172:175], v[202:205], 0
	v_mfma_f32_16x16x32_bf16 v[74:77], v[164:167], v[210:213], 0
	v_mfma_f32_16x16x32_bf16 v[66:69], v[172:175], v[210:213], 0
	v_mfma_f32_16x16x32_bf16 v[122:125], v[168:171], v[184:187], v[122:125]
	v_mfma_f32_16x16x32_bf16 v[114:117], v[176:179], v[184:187], v[114:117]
	v_mfma_f32_16x16x32_bf16 v[106:109], v[168:171], v[192:195], v[106:109]
	v_mfma_f32_16x16x32_bf16 v[98:101], v[176:179], v[192:195], v[98:101]
	v_mfma_f32_16x16x32_bf16 v[90:93], v[168:171], v[206:209], v[90:93]
	v_mfma_f32_16x16x32_bf16 v[82:85], v[176:179], v[206:209], v[82:85]
	v_mfma_f32_16x16x32_bf16 v[74:77], v[168:171], v[214:217], v[74:77]
	v_mfma_f32_16x16x32_bf16 v[66:69], v[176:179], v[214:217], v[66:69]
	s_setprio 0
	s_barrier
	s_add_i32 s58, s58, s3
	v_lshl_add_u64 v[154:155], s[56:57], 0, v[136:137]
	s_mov_b32 m0, s58
	ds_read_b128 v[180:183], v158 offset:16384
	ds_read_b128 v[184:187], v158 offset:17408
	ds_read_b128 v[188:191], v158 offset:18432
	ds_read_b128 v[192:195], v158 offset:19456
	ds_read_b128 v[202:205], v158 offset:20480
	ds_read_b128 v[206:209], v158 offset:21504
	ds_read_b128 v[210:213], v158 offset:22528
	ds_read_b128 v[214:217], v158 offset:23552
	global_load_lds_dwordx4 v[154:155], off
	s_add_i32 m0, s58, 0x2000
	v_lshl_add_u64 v[196:197], s[56:57], 0, v[140:141]
	s_add_u32 s56, s56, s70
	s_addc_u32 s57, s57, 0
	s_add_i32 s34, s34, s3
	global_load_lds_dwordx4 v[196:197], off
	v_lshl_add_u64 v[218:219], s[56:57], 0, v[136:137]
	s_mov_b32 m0, s34
	v_lshl_add_u64 v[220:221], s[56:57], 0, v[140:141]
	global_load_lds_dwordx4 v[218:219], off
	s_add_i32 m0, s34, 0x2000
	v_lshl_add_u64 v[222:223], s[46:47], 0, v[134:135]
	global_load_lds_dwordx4 v[220:221], off
	s_mov_b32 m0, s4
	v_lshl_add_u64 v[224:225], s[46:47], 0, v[138:139]
	global_load_lds_dwordx4 v[222:223], off
	s_mov_b32 m0, s19
	s_nop 0
	global_load_lds_dwordx4 v[224:225], off
	s_waitcnt vmcnt(8)
	s_waitcnt lgkmcnt(0)
	s_barrier
; #define PG8_STAGE(bufoff, gbase, voff) do { _Pragma("unroll") for (int _i = 0; _i < 2; ++_i) \
;         __builtin_amdgcn_global_load_lds((const unsigned*)((const char*)(gbase) + (voff)[_i]), (PG8_LAS unsigned*)(lds + (bufoff) + ldsw + _i * 8192), 16, 0, 0); } while (0)
; #define PG8_LDA(dst, b, h) do { _Pragma("unroll") for (int m = 0; m < 4; ++m) _Pragma("unroll") for (int k = 0; k < 2; ++k) dst[m][k] = *(const PG8_LAS bf16x8*)(lds + PG8_SA(b, h) + aoff + m * 2048 + k * 1024); } while (0)
; #define PG8_LDB(dst, b, h) do { _Pragma("unroll") for (int n = 0; n < 2; ++n) _Pragma("unroll") for (int k = 0; k < 2; ++k) dst[n][k] = *(const PG8_LAS bf16x8*)(lds + PG8_SB(b, h) + boff + n * 2048 + k * 1024); } while (0)
; #define PG8_MMA(ai, bj, At, Bt) do { __builtin_amdgcn_s_setprio(1); _Pragma("unroll") for (int m = 0; m < 4; ++m) _Pragma("unroll") for (int n = 0; n < 2; ++n) _Pragma("unroll") for (int k = 0; k < 2; ++k) \
;         acc[ai][bj][m][n] = __builtin_amdgcn_mfma_f32_16x16x32_bf16(Bt[n][k], At[m][k], acc[ai][bj][m][n], 0, 0, 0); __builtin_amdgcn_s_setprio(0); } while (0)
; #define PG8_WAIT_V(n) asm volatile("s_waitcnt vmcnt(" #n ")" ::: "memory")
; #define PG8_WAIT_L(n) asm volatile("s_waitcnt lgkmcnt(" #n ")" ::: "memory")
; #define PG8_BAR __builtin_amdgcn_s_barrier()
; #define PG8_SCHED __builtin_amdgcn_sched_barrier(0)
; template <class Epi, class Sched>
; __device__ __forceinline__ void gemm_phase(PG8_LAS unsigned char* lds, const Gemm g, const Sched& S, const Epi& E) {
;     ...
;             PG8_WAIT_V(8); PG8_WAIT_L(0); PG8_BAR; PG8_MMA(1, 0, At, B0); PG8_MMA(1, 1, At, B1); PG8_BAR; PG8_SCHED;
;             PG8_LDB(B0, 1, 0); PG8_LDB(B1, 1, 1); PG8_SCHED; PG8_LDA(At, 1, 0); PG8_STAGE(PG8_SA(0, 1), a2 + hstep, voffA);
;             PG8_WAIT_V(8); PG8_WAIT_L(0); PG8_BAR; PG8_MMA(0, 0, At, B0); PG8_MMA(0, 1, At, B1); PG8_BAR; PG8_SCHED;
	s_setprio 1
	s_waitcnt lgkmcnt(0)
	v_mfma_f32_16x16x32_bf16 v[62:65], v[130:133], v[180:183], 0
	v_mfma_f32_16x16x32_bf16 v[54:57], v[150:153], v[180:183], 0
	v_mfma_f32_16x16x32_bf16 v[46:49], v[130:133], v[188:191], 0
	v_mfma_f32_16x16x32_bf16 v[38:41], v[150:153], v[188:191], 0
	v_mfma_f32_16x16x32_bf16 v[30:33], v[130:133], v[202:205], 0
	v_mfma_f32_16x16x32_bf16 v[22:25], v[150:153], v[202:205], 0
	v_mfma_f32_16x16x32_bf16 v[14:17], v[130:133], v[210:213], 0
	v_mfma_f32_16x16x32_bf16 v[6:9], v[150:153], v[210:213], 0
	v_mfma_f32_16x16x32_bf16 v[62:65], v[146:149], v[184:187], v[62:65]
	v_mfma_f32_16x16x32_bf16 v[54:57], v[160:163], v[184:187], v[54:57]
	v_mfma_f32_16x16x32_bf16 v[46:49], v[146:149], v[192:195], v[46:49]
	v_mfma_f32_16x16x32_bf16 v[38:41], v[160:163], v[192:195], v[38:41]
	v_mfma_f32_16x16x32_bf16 v[30:33], v[146:149], v[206:209], v[30:33]
	v_mfma_f32_16x16x32_bf16 v[22:25], v[160:163], v[206:209], v[22:25]
	v_mfma_f32_16x16x32_bf16 v[14:17], v[146:149], v[214:217], v[14:17]
	v_mfma_f32_16x16x32_bf16 v[6:9], v[160:163], v[214:217], v[6:9]
	s_setprio 0
	s_setprio 1
	v_mfma_f32_16x16x32_bf16 v[58:61], v[164:167], v[180:183], 0
	v_mfma_f32_16x16x32_bf16 v[50:53], v[172:175], v[180:183], 0
	v_mfma_f32_16x16x32_bf16 v[42:45], v[164:167], v[188:191], 0
	v_mfma_f32_16x16x32_bf16 v[34:37], v[172:175], v[188:191], 0
	v_mfma_f32_16x16x32_bf16 v[26:29], v[164:167], v[202:205], 0
	v_mfma_f32_16x16x32_bf16 v[18:21], v[172:175], v[202:205], 0
	v_mfma_f32_16x16x32_bf16 v[10:13], v[164:167], v[210:213], 0
	v_mfma_f32_16x16x32_bf16 v[2:5], v[172:175], v[210:213], 0
	v_mfma_f32_16x16x32_bf16 v[58:61], v[168:171], v[184:187], v[58:61]
	v_mfma_f32_16x16x32_bf16 v[50:53], v[176:179], v[184:187], v[50:53]
	v_mfma_f32_16x16x32_bf16 v[42:45], v[168:171], v[192:195], v[42:45]
	v_mfma_f32_16x16x32_bf16 v[34:37], v[176:179], v[192:195], v[34:37]
	v_mfma_f32_16x16x32_bf16 v[26:29], v[168:171], v[206:209], v[26:29]
	v_mfma_f32_16x16x32_bf16 v[18:21], v[176:179], v[206:209], v[18:21]
	v_mfma_f32_16x16x32_bf16 v[10:13], v[168:171], v[214:217], v[10:13]
	v_mfma_f32_16x16x32_bf16 v[2:5], v[176:179], v[214:217], v[2:5]
	s_setprio 0
	s_barrier
	s_add_i32 s34, 0, 0x18000
	v_add_u32_e32 v159, s34, v157
	s_add_i32 s56, 0, 0x1c000
	ds_read_b128 v[130:133], v159
	ds_read_b128 v[146:149], v159 offset:1024
	ds_read_b128 v[150:153], v159 offset:2048
	ds_read_b128 v[160:163], v159 offset:3072
	v_add_u32_e32 v159, s56, v157
	ds_read_b128 v[164:167], v159
	ds_read_b128 v[168:171], v159 offset:1024
	ds_read_b128 v[172:175], v159 offset:2048
	ds_read_b128 v[176:179], v159 offset:3072
	s_add_u32 s46, s46, s70
	s_addc_u32 s47, s47, 0
	s_mov_b32 m0, s22
	v_lshl_add_u64 v[226:227], s[46:47], 0, v[134:135]
	ds_read_b128 v[180:183], v158 offset:32768
	ds_read_b128 v[184:187], v158 offset:33792
	ds_read_b128 v[188:191], v158 offset:34816
	ds_read_b128 v[192:195], v158 offset:35840
	ds_read_b128 v[202:205], v158 offset:36864
	ds_read_b128 v[206:209], v158 offset:37888
	ds_read_b128 v[210:213], v158 offset:38912
	ds_read_b128 v[214:217], v158 offset:39936
	global_load_lds_dwordx4 v[226:227], off
	v_lshl_add_u64 v[226:227], s[46:47], 0, v[138:139]
	s_mov_b32 m0, s24
	s_nop 0
	global_load_lds_dwordx4 v[226:227], off
	s_waitcnt vmcnt(8)
	s_waitcnt lgkmcnt(0)
	s_barrier
	s_setprio 1
	s_waitcnt lgkmcnt(0)
	v_mfma_f32_16x16x32_bf16 v[126:129], v[130:133], v[180:183], v[126:129]
	v_mfma_f32_16x16x32_bf16 v[118:121], v[150:153], v[180:183], v[118:121]
	v_mfma_f32_16x16x32_bf16 v[110:113], v[130:133], v[188:191], v[110:113]
	v_mfma_f32_16x16x32_bf16 v[102:105], v[150:153], v[188:191], v[102:105]
	v_mfma_f32_16x16x32_bf16 v[94:97], v[130:133], v[202:205], v[94:97]
	v_mfma_f32_16x16x32_bf16 v[86:89], v[150:153], v[202:205], v[86:89]
	v_mfma_f32_16x16x32_bf16 v[78:81], v[130:133], v[210:213], v[78:81]
	v_mfma_f32_16x16x32_bf16 v[70:73], v[150:153], v[210:213], v[70:73]
	v_mfma_f32_16x16x32_bf16 v[126:129], v[146:149], v[184:187], v[126:129]
	v_mfma_f32_16x16x32_bf16 v[118:121], v[160:163], v[184:187], v[118:121]
	v_mfma_f32_16x16x32_bf16 v[110:113], v[146:149], v[192:195], v[110:113]
	v_mfma_f32_16x16x32_bf16 v[102:105], v[160:163], v[192:195], v[102:105]
	v_mfma_f32_16x16x32_bf16 v[94:97], v[146:149], v[206:209], v[94:97]
	v_mfma_f32_16x16x32_bf16 v[86:89], v[160:163], v[206:209], v[86:89]
	v_mfma_f32_16x16x32_bf16 v[78:81], v[146:149], v[214:217], v[78:81]
	v_mfma_f32_16x16x32_bf16 v[70:73], v[160:163], v[214:217], v[70:73]
	s_setprio 0
	s_setprio 1
	v_mfma_f32_16x16x32_bf16 v[122:125], v[164:167], v[180:183], v[122:125]
	v_mfma_f32_16x16x32_bf16 v[114:117], v[172:175], v[180:183], v[114:117]
	v_mfma_f32_16x16x32_bf16 v[106:109], v[164:167], v[188:191], v[106:109]
	v_mfma_f32_16x16x32_bf16 v[98:101], v[172:175], v[188:191], v[98:101]
	v_mfma_f32_16x16x32_bf16 v[90:93], v[164:167], v[202:205], v[90:93]
	v_mfma_f32_16x16x32_bf16 v[82:85], v[172:175], v[202:205], v[82:85]
	v_mfma_f32_16x16x32_bf16 v[74:77], v[164:167], v[210:213], v[74:77]
	v_mfma_f32_16x16x32_bf16 v[66:69], v[172:175], v[210:213], v[66:69]
	v_mfma_f32_16x16x32_bf16 v[122:125], v[168:171], v[184:187], v[122:125]
	v_mfma_f32_16x16x32_bf16 v[114:117], v[176:179], v[184:187], v[114:117]
	v_mfma_f32_16x16x32_bf16 v[106:109], v[168:171], v[192:195], v[106:109]
	v_mfma_f32_16x16x32_bf16 v[98:101], v[176:179], v[192:195], v[98:101]
	v_mfma_f32_16x16x32_bf16 v[90:93], v[168:171], v[206:209], v[90:93]
	v_mfma_f32_16x16x32_bf16 v[82:85], v[176:179], v[206:209], v[82:85]
	v_mfma_f32_16x16x32_bf16 v[74:77], v[168:171], v[214:217], v[74:77]
	v_mfma_f32_16x16x32_bf16 v[66:69], v[176:179], v[214:217], v[66:69]
	s_setprio 0
	s_barrier
; #define PG8_STAGE(bufoff, gbase, voff) do { _Pragma("unroll") for (int _i = 0; _i < 2; ++_i) \
;         __builtin_amdgcn_global_load_lds((const unsigned*)((const char*)(gbase) + (voff)[_i]), (PG8_LAS unsigned*)(lds + (bufoff) + ldsw + _i * 8192), 16, 0, 0); } while (0)
; #define PG8_LDA(dst, b, h) do { _Pragma("unroll") for (int m = 0; m < 4; ++m) _Pragma("unroll") for (int k = 0; k < 2; ++k) dst[m][k] = *(const PG8_LAS bf16x8*)(lds + PG8_SA(b, h) + aoff + m * 2048 + k * 1024); } while (0)
; #define PG8_MMA(ai, bj, At, Bt) do { __builtin_amdgcn_s_setprio(1); _Pragma("unroll") for (int m = 0; m < 4; ++m) _Pragma("unroll") for (int n = 0; n < 2; ++n) _Pragma("unroll") for (int k = 0; k < 2; ++k) \
;         acc[ai][bj][m][n] = __builtin_amdgcn_mfma_f32_16x16x32_bf16(Bt[n][k], At[m][k], acc[ai][bj][m][n], 0, 0, 0); __builtin_amdgcn_s_setprio(0); } while (0)
; #define PG8_WAIT_V(n) asm volatile("s_waitcnt vmcnt(" #n ")" ::: "memory")
; #define PG8_WAIT_L(n) asm volatile("s_waitcnt lgkmcnt(" #n ")" ::: "memory")
; #define PG8_BAR __builtin_amdgcn_s_barrier()
; #define PG8_SCHED __builtin_amdgcn_sched_barrier(0)
; template <class Epi, class Sched>
; __device__ __forceinline__ void gemm_phase(PG8_LAS unsigned char* lds, const Gemm g, const Sched& S, const Epi& E) {
;     ...
;             PG8_LDA(At, 1, 1); PG8_STAGE(PG8_SB(1, 0), b3, voffB); PG8_STAGE(PG8_SB(1, 1), b3 + hstep, voffB); PG8_STAGE(PG8_SA(1, 0), a3, voffA);
;             PG8_WAIT_V(8); PG8_WAIT_L(0); PG8_BAR; PG8_MMA(1, 0, At, B0); PG8_MMA(1, 1, At, B1); PG8_BAR; PG8_SCHED;
;         }
	s_add_i32 s34, s34, s3
	v_lshl_add_u64 v[154:155], v[154:155], 0, s[0:1]
	s_mov_b32 m0, s34
	ds_read_b128 v[180:183], v158 offset:49152
	ds_read_b128 v[184:187], v158 offset:50176
	ds_read_b128 v[188:191], v158 offset:51200
	ds_read_b128 v[192:195], v158 offset:52224
	ds_read_b128 v[202:205], v158 offset:53248
	ds_read_b128 v[206:209], v158 offset:54272
	ds_read_b128 v[210:213], v158 offset:55296
	ds_read_b128 v[214:217], v158 offset:56320
	global_load_lds_dwordx4 v[154:155], off
	v_lshl_add_u64 v[154:155], v[196:197], 0, s[0:1]
	s_add_i32 m0, s34, 0x2000
	s_add_i32 s34, s56, s3
	global_load_lds_dwordx4 v[154:155], off
	v_lshl_add_u64 v[154:155], v[218:219], 0, s[0:1]
	s_mov_b32 m0, s34
	s_nop 0
	global_load_lds_dwordx4 v[154:155], off
	v_lshl_add_u64 v[154:155], v[220:221], 0, s[0:1]
	s_add_i32 m0, s34, 0x2000
	s_nop 0
	global_load_lds_dwordx4 v[154:155], off
	v_lshl_add_u64 v[154:155], v[222:223], 0, s[0:1]
	s_mov_b32 m0, s37
	s_nop 0
	global_load_lds_dwordx4 v[154:155], off
	v_lshl_add_u64 v[154:155], v[224:225], 0, s[0:1]
	s_mov_b32 m0, s38
	s_nop 0
	global_load_lds_dwordx4 v[154:155], off
	s_waitcnt vmcnt(8)
	s_waitcnt lgkmcnt(0)
	s_barrier
	s_setprio 1
	s_waitcnt lgkmcnt(0)
	v_mfma_f32_16x16x32_bf16 v[62:65], v[130:133], v[180:183], v[62:65]
	v_mfma_f32_16x16x32_bf16 v[54:57], v[150:153], v[180:183], v[54:57]
	v_mfma_f32_16x16x32_bf16 v[46:49], v[130:133], v[188:191], v[46:49]
	v_mfma_f32_16x16x32_bf16 v[38:41], v[150:153], v[188:191], v[38:41]
	v_mfma_f32_16x16x32_bf16 v[30:33], v[130:133], v[202:205], v[30:33]
	v_mfma_f32_16x16x32_bf16 v[22:25], v[150:153], v[202:205], v[22:25]
	v_mfma_f32_16x16x32_bf16 v[14:17], v[130:133], v[210:213], v[14:17]
	v_mfma_f32_16x16x32_bf16 v[6:9], v[150:153], v[210:213], v[6:9]
	v_mfma_f32_16x16x32_bf16 v[62:65], v[146:149], v[184:187], v[62:65]
	v_mfma_f32_16x16x32_bf16 v[54:57], v[160:163], v[184:187], v[54:57]
	v_mfma_f32_16x16x32_bf16 v[46:49], v[146:149], v[192:195], v[46:49]
	v_mfma_f32_16x16x32_bf16 v[38:41], v[160:163], v[192:195], v[38:41]
	v_mfma_f32_16x16x32_bf16 v[30:33], v[146:149], v[206:209], v[30:33]
	v_mfma_f32_16x16x32_bf16 v[22:25], v[160:163], v[206:209], v[22:25]
	v_mfma_f32_16x16x32_bf16 v[14:17], v[146:149], v[214:217], v[14:17]
	v_mfma_f32_16x16x32_bf16 v[6:9], v[160:163], v[214:217], v[6:9]
	s_setprio 0
	s_setprio 1
	v_mfma_f32_16x16x32_bf16 v[58:61], v[164:167], v[180:183], v[58:61]
	v_mfma_f32_16x16x32_bf16 v[50:53], v[172:175], v[180:183], v[50:53]
	v_mfma_f32_16x16x32_bf16 v[42:45], v[164:167], v[188:191], v[42:45]
	v_mfma_f32_16x16x32_bf16 v[34:37], v[172:175], v[188:191], v[34:37]
	v_mfma_f32_16x16x32_bf16 v[26:29], v[164:167], v[202:205], v[26:29]
	v_mfma_f32_16x16x32_bf16 v[18:21], v[172:175], v[202:205], v[18:21]
	v_mfma_f32_16x16x32_bf16 v[10:13], v[164:167], v[210:213], v[10:13]
	v_mfma_f32_16x16x32_bf16 v[2:5], v[172:175], v[210:213], v[2:5]
	v_mfma_f32_16x16x32_bf16 v[58:61], v[168:171], v[184:187], v[58:61]
	v_mfma_f32_16x16x32_bf16 v[50:53], v[176:179], v[184:187], v[50:53]
	v_mfma_f32_16x16x32_bf16 v[42:45], v[168:171], v[192:195], v[42:45]
	v_mfma_f32_16x16x32_bf16 v[34:37], v[176:179], v[192:195], v[34:37]
	v_mfma_f32_16x16x32_bf16 v[26:29], v[168:171], v[206:209], v[26:29]
	v_mfma_f32_16x16x32_bf16 v[18:21], v[176:179], v[206:209], v[18:21]
	v_mfma_f32_16x16x32_bf16 v[10:13], v[168:171], v[214:217], v[10:13]
	v_mfma_f32_16x16x32_bf16 v[2:5], v[176:179], v[214:217], v[2:5]
	s_setprio 0
	s_barrier
	s_add_u32 s42, s42, 0x100
	s_addc_u32 s43, s43, 0
	s_add_u32 s14, s14, 0x100
	s_addc_u32 s15, s15, 0
	s_cmp_ge_u32 s55, s33
	s_mov_b32 s34, s55
	.p2align	6

; template <class Epi, class Sched>
; __device__ __forceinline__ void gemm_phase(PG8_LAS unsigned char* lds, const Gemm g, const Sched& S, const Epi& E) {
;     ...
;         const bool has_next = S.next(ui + 1, nxt);
;         const char* nA = has_next ? (const char*)g.A + (size_t)nxt.pm * tstep : cA; const char* nB = has_next ? (const char*)g.Bt + (size_t)nxt.pn * tstep : cB;
;         for (int t = 0; t < nt; t += 2) {
;             const bool last = (t == nt - 2);
;             const char* a1 = cA + (size_t)(t + 1) * kstep;
;             const char* a2 = last ? nA : cA + (size_t)(t + 2) * kstep; const char* b2 = last ? nB : cB + (size_t)(t + 2) * kstep;
.LBB0_386:
	s_add_u32 s44, s44, 0x80
	s_addc_u32 s45, s45, 0
	s_add_u32 s34, s42, 0x100
	s_addc_u32 s35, s43, 0
	s_mov_b32 s42, 0
	.p2align	6

; #define PG8_STAGE(bufoff, gbase, voff) do { _Pragma("unroll") for (int _i = 0; _i < 2; ++_i) \
;         __builtin_amdgcn_global_load_lds((const unsigned*)((const char*)(gbase) + (voff)[_i]), (PG8_LAS unsigned*)(lds + (bufoff) + ldsw + _i * 8192), 16, 0, 0); } while (0)
; #define PG8_LDA(dst, b, h) do { _Pragma("unroll") for (int m = 0; m < 4; ++m) _Pragma("unroll") for (int k = 0; k < 2; ++k) dst[m][k] = *(const PG8_LAS bf16x8*)(lds + PG8_SA(b, h) + aoff + m * 2048 + k * 1024); } while (0)
; #define PG8_LDB(dst, b, h) do { _Pragma("unroll") for (int n = 0; n < 2; ++n) _Pragma("unroll") for (int k = 0; k < 2; ++k) dst[n][k] = *(const PG8_LAS bf16x8*)(lds + PG8_SB(b, h) + boff + n * 2048 + k * 1024); } while (0)
; #define PG8_MMA(ai, bj, At, Bt) do { __builtin_amdgcn_s_setprio(1); _Pragma("unroll") for (int m = 0; m < 4; ++m) _Pragma("unroll") for (int n = 0; n < 2; ++n) _Pragma("unroll") for (int k = 0; k < 2; ++k) \
;         acc[ai][bj][m][n] = __builtin_amdgcn_mfma_f32_16x16x32_bf16(Bt[n][k], At[m][k], acc[ai][bj][m][n], 0, 0, 0); __builtin_amdgcn_s_setprio(0); } while (0)
; #define PG8_BAR __builtin_amdgcn_s_barrier()
; template <class Epi, class Sched>
; __device__ __forceinline__ void gemm_phase(PG8_LAS unsigned char* lds, const Gemm g, const Sched& S, const Epi& E) {
;     ...
;         const bool has_next = S.next(ui + 1, nxt);
;         const char* nA = has_next ? (const char*)g.A + (size_t)nxt.pm * tstep : cA; const char* nB = has_next ? (const char*)g.Bt + (size_t)nxt.pn * tstep : cB;
;         for (int t = 0; t < nt; t += 2) {
;             const bool last = (t == nt - 2);
;             const char* a1 = cA + (size_t)(t + 1) * kstep;
;             const char* a2 = last ? nA : cA + (size_t)(t + 2) * kstep; const char* b2 = last ? nB : cB + (size_t)(t + 2) * kstep;
;             const char* a3 = a2 + kstep; const char* b3 = b2 + kstep;
;             PG8_LDB(B0, 0, 0); PG8_LDB(B1, 0, 1); PG8_SCHED; PG8_LDA(At, 0, 0); PG8_STAGE(PG8_SA(1, 1), a1 + hstep, voffA);
;             PG8_WAIT_V(8); PG8_WAIT_L(0); PG8_BAR; PG8_MMA(0, 0, At, B0); PG8_MMA(0, 1, At, B1); PG8_BAR; PG8_SCHED;
;             PG8_LDA(At, 0, 1); PG8_STAGE(PG8_SB(0, 0), b2, voffB); PG8_STAGE(PG8_SB(0, 1), b2 + hstep, voffB); PG8_STAGE(PG8_SA(0, 0), a2, voffA);
;             PG8_WAIT_V(8); PG8_WAIT_L(0); PG8_BAR; PG8_MMA(1, 0, At, B0); PG8_MMA(1, 1, At, B1); PG8_BAR; PG8_SCHED;
.LBB0_517:
	s_add_u32 s44, s44, 0x80
	s_addc_u32 s45, s45, 0
	s_add_u32 s14, s46, 0x100
	s_addc_u32 s15, s47, 0
	s_mov_b32 s18, 0
	s_waitcnt vmcnt(0)
	s_add_i32 s34, s18, 2
	s_add_u32 s35, s44, 0x80
	s_addc_u32 s46, s45, 0
	s_add_i32 s50, 0, 0x10000
	s_cmp_eq_u32 s38, s18
	s_cselect_b32 s47, s27, s46
	s_cselect_b32 s46, s26, s35
	v_add_u32_e32 v1, s50, v218
	s_cselect_b32 s49, s43, s15
	s_cselect_b32 s48, s42, s14
	s_add_i32 s18, 0, 0x14000
	s_waitcnt lgkmcnt(0)
	ds_read_b128 v[130:133], v1
	ds_read_b128 v[134:137], v1 offset:1024
	ds_read_b128 v[138:141], v1 offset:2048
	ds_read_b128 v[142:145], v1 offset:3072
	v_add_u32_e32 v1, s18, v218
	ds_read_b128 v[146:149], v1
	ds_read_b128 v[150:153], v1 offset:1024
	ds_read_b128 v[154:157], v1 offset:2048
	ds_read_b128 v[158:161], v1 offset:3072
	v_lshl_add_u64 v[212:213], s[44:45], 0, v[208:209]
	s_add_i32 m0, s22, 0xc000
	ds_read_b128 v[162:165], v219
	ds_read_b128 v[166:169], v219 offset:1024
	ds_read_b128 v[170:173], v219 offset:2048
	ds_read_b128 v[174:177], v219 offset:3072
	ds_read_b128 v[178:181], v219 offset:4096
	ds_read_b128 v[182:185], v219 offset:5120
	ds_read_b128 v[186:189], v219 offset:6144
	ds_read_b128 v[190:193], v219 offset:7168
	global_load_lds_dwordx4 v[212:213], off
	v_lshl_add_u64 v[212:213], s[44:45], 0, v[210:211]
	s_add_i32 m0, s22, 0xe000
	s_nop 0
	global_load_lds_dwordx4 v[212:213], off
	s_waitcnt vmcnt(8)
	s_waitcnt lgkmcnt(0)
	s_barrier
	s_setprio 1
	s_waitcnt lgkmcnt(0)
	v_mfma_f32_16x16x32_bf16 v[126:129], v[130:133], v[162:165], 0
	v_mfma_f32_16x16x32_bf16 v[122:125], v[138:141], v[162:165], 0
	v_mfma_f32_16x16x32_bf16 v[118:121], v[130:133], v[170:173], 0
	v_mfma_f32_16x16x32_bf16 v[114:117], v[138:141], v[170:173], 0
	v_mfma_f32_16x16x32_bf16 v[110:113], v[130:133], v[178:181], 0
	v_mfma_f32_16x16x32_bf16 v[106:109], v[138:141], v[178:181], 0
	v_mfma_f32_16x16x32_bf16 v[102:105], v[130:133], v[186:189], 0
	v_mfma_f32_16x16x32_bf16 v[98:101], v[138:141], v[186:189], 0
	v_mfma_f32_16x16x32_bf16 v[126:129], v[134:137], v[166:169], v[126:129]
	v_mfma_f32_16x16x32_bf16 v[122:125], v[142:145], v[166:169], v[122:125]
	v_mfma_f32_16x16x32_bf16 v[118:121], v[134:137], v[174:177], v[118:121]
	v_mfma_f32_16x16x32_bf16 v[114:117], v[142:145], v[174:177], v[114:117]
	v_mfma_f32_16x16x32_bf16 v[110:113], v[134:137], v[182:185], v[110:113]
	v_mfma_f32_16x16x32_bf16 v[106:109], v[142:145], v[182:185], v[106:109]
	v_mfma_f32_16x16x32_bf16 v[102:105], v[134:137], v[190:193], v[102:105]
	v_mfma_f32_16x16x32_bf16 v[98:101], v[142:145], v[190:193], v[98:101]
	s_setprio 0
	s_setprio 1
	v_mfma_f32_16x16x32_bf16 v[94:97], v[146:149], v[162:165], 0
	v_mfma_f32_16x16x32_bf16 v[90:93], v[154:157], v[162:165], 0
	v_mfma_f32_16x16x32_bf16 v[86:89], v[146:149], v[170:173], 0
	v_mfma_f32_16x16x32_bf16 v[82:85], v[154:157], v[170:173], 0
	v_mfma_f32_16x16x32_bf16 v[78:81], v[146:149], v[178:181], 0
	v_mfma_f32_16x16x32_bf16 v[74:77], v[154:157], v[178:181], 0
	v_mfma_f32_16x16x32_bf16 v[70:73], v[146:149], v[186:189], 0
	v_mfma_f32_16x16x32_bf16 v[66:69], v[154:157], v[186:189], 0
	v_mfma_f32_16x16x32_bf16 v[94:97], v[150:153], v[166:169], v[94:97]
	v_mfma_f32_16x16x32_bf16 v[90:93], v[158:161], v[166:169], v[90:93]
	v_mfma_f32_16x16x32_bf16 v[86:89], v[150:153], v[174:177], v[86:89]
	v_mfma_f32_16x16x32_bf16 v[82:85], v[158:161], v[174:177], v[82:85]
	v_mfma_f32_16x16x32_bf16 v[78:81], v[150:153], v[182:185], v[78:81]
	v_mfma_f32_16x16x32_bf16 v[74:77], v[158:161], v[182:185], v[74:77]
	v_mfma_f32_16x16x32_bf16 v[70:73], v[150:153], v[190:193], v[70:73]
	v_mfma_f32_16x16x32_bf16 v[66:69], v[158:161], v[190:193], v[66:69]
	s_setprio 0
	s_barrier
	s_add_i32 s35, s50, s25
	v_lshl_add_u64 v[212:213], s[48:49], 0, v[202:203]
	s_mov_b32 m0, s35
	ds_read_b128 v[162:165], v219 offset:16384
	ds_read_b128 v[166:169], v219 offset:17408
	ds_read_b128 v[170:173], v219 offset:18432
	ds_read_b128 v[174:177], v219 offset:19456
	ds_read_b128 v[178:181], v219 offset:20480
	ds_read_b128 v[182:185], v219 offset:21504
	ds_read_b128 v[186:189], v219 offset:22528
	ds_read_b128 v[190:193], v219 offset:23552
	global_load_lds_dwordx4 v[212:213], off
	s_add_i32 m0, s35, 0x2000
	v_lshl_add_u64 v[214:215], s[48:49], 0, v[206:207]
	s_add_u32 s48, s48, s70
	s_addc_u32 s49, s49, 0
	s_add_i32 s18, s18, s25
	global_load_lds_dwordx4 v[214:215], off
	v_lshl_add_u64 v[216:217], s[48:49], 0, v[202:203]
	s_mov_b32 m0, s18
	v_lshl_add_u64 v[220:221], s[48:49], 0, v[206:207]
	global_load_lds_dwordx4 v[216:217], off
	s_add_i32 m0, s18, 0x2000
	v_lshl_add_u64 v[222:223], s[46:47], 0, v[194:195]
	global_load_lds_dwordx4 v[220:221], off
	s_mov_b32 m0, s22
	v_lshl_add_u64 v[224:225], s[46:47], 0, v[204:205]
	global_load_lds_dwordx4 v[222:223], off
	s_mov_b32 m0, s92
	s_nop 0
	global_load_lds_dwordx4 v[224:225], off
	s_waitcnt vmcnt(8)
	s_waitcnt lgkmcnt(0)
	s_barrier
; #define PG8_STAGE(bufoff, gbase, voff) do { _Pragma("unroll") for (int _i = 0; _i < 2; ++_i) \
;         __builtin_amdgcn_global_load_lds((const unsigned*)((const char*)(gbase) + (voff)[_i]), (PG8_LAS unsigned*)(lds + (bufoff) + ldsw + _i * 8192), 16, 0, 0); } while (0)
; #define PG8_LDA(dst, b, h) do { _Pragma("unroll") for (int m = 0; m < 4; ++m) _Pragma("unroll") for (int k = 0; k < 2; ++k) dst[m][k] = *(const PG8_LAS bf16x8*)(lds + PG8_SA(b, h) + aoff + m * 2048 + k * 1024); } while (0)
; #define PG8_LDB(dst, b, h) do { _Pragma("unroll") for (int n = 0; n < 2; ++n) _Pragma("unroll") for (int k = 0; k < 2; ++k) dst[n][k] = *(const PG8_LAS bf16x8*)(lds + PG8_SB(b, h) + boff + n * 2048 + k * 1024); } while (0)
; #define PG8_MMA(ai, bj, At, Bt) do { __builtin_amdgcn_s_setprio(1); _Pragma("unroll") for (int m = 0; m < 4; ++m) _Pragma("unroll") for (int n = 0; n < 2; ++n) _Pragma("unroll") for (int k = 0; k < 2; ++k) \
;         acc[ai][bj][m][n] = __builtin_amdgcn_mfma_f32_16x16x32_bf16(Bt[n][k], At[m][k], acc[ai][bj][m][n], 0, 0, 0); __builtin_amdgcn_s_setprio(0); } while (0)
; #define PG8_WAIT_V(n) asm volatile("s_waitcnt vmcnt(" #n ")" ::: "memory")
; #define PG8_WAIT_L(n) asm volatile("s_waitcnt lgkmcnt(" #n ")" ::: "memory")
; #define PG8_BAR __builtin_amdgcn_s_barrier()
; #define PG8_SCHED __builtin_amdgcn_sched_barrier(0)
; template <class Epi, class Sched>
; __device__ __forceinline__ void gemm_phase(PG8_LAS unsigned char* lds, const Gemm g, const Sched& S, const Epi& E) {
;     ...
;             PG8_WAIT_V(8); PG8_WAIT_L(0); PG8_BAR; PG8_MMA(1, 0, At, B0); PG8_MMA(1, 1, At, B1); PG8_BAR; PG8_SCHED;
;             PG8_LDB(B0, 1, 0); PG8_LDB(B1, 1, 1); PG8_SCHED; PG8_LDA(At, 1, 0); PG8_STAGE(PG8_SA(0, 1), a2 + hstep, voffA);
;             PG8_WAIT_V(8); PG8_WAIT_L(0); PG8_BAR; PG8_MMA(0, 0, At, B0); PG8_MMA(0, 1, At, B1); PG8_BAR; PG8_SCHED;
	s_setprio 1
	s_waitcnt lgkmcnt(0)
	v_mfma_f32_16x16x32_bf16 v[62:65], v[130:133], v[162:165], 0
	v_mfma_f32_16x16x32_bf16 v[58:61], v[138:141], v[162:165], 0
	v_mfma_f32_16x16x32_bf16 v[54:57], v[130:133], v[170:173], 0
	v_mfma_f32_16x16x32_bf16 v[50:53], v[138:141], v[170:173], 0
	v_mfma_f32_16x16x32_bf16 v[46:49], v[130:133], v[178:181], 0
	v_mfma_f32_16x16x32_bf16 v[42:45], v[138:141], v[178:181], 0
	v_mfma_f32_16x16x32_bf16 v[38:41], v[130:133], v[186:189], 0
	v_mfma_f32_16x16x32_bf16 v[34:37], v[138:141], v[186:189], 0
	v_mfma_f32_16x16x32_bf16 v[62:65], v[134:137], v[166:169], v[62:65]
	v_mfma_f32_16x16x32_bf16 v[58:61], v[142:145], v[166:169], v[58:61]
	v_mfma_f32_16x16x32_bf16 v[54:57], v[134:137], v[174:177], v[54:57]
	v_mfma_f32_16x16x32_bf16 v[50:53], v[142:145], v[174:177], v[50:53]
	v_mfma_f32_16x16x32_bf16 v[46:49], v[134:137], v[182:185], v[46:49]
	v_mfma_f32_16x16x32_bf16 v[42:45], v[142:145], v[182:185], v[42:45]
	v_mfma_f32_16x16x32_bf16 v[38:41], v[134:137], v[190:193], v[38:41]
	v_mfma_f32_16x16x32_bf16 v[34:37], v[142:145], v[190:193], v[34:37]
	s_setprio 0
	s_setprio 1
	v_mfma_f32_16x16x32_bf16 v[30:33], v[146:149], v[162:165], 0
	v_mfma_f32_16x16x32_bf16 v[26:29], v[154:157], v[162:165], 0
	v_mfma_f32_16x16x32_bf16 v[22:25], v[146:149], v[170:173], 0
	v_mfma_f32_16x16x32_bf16 v[18:21], v[154:157], v[170:173], 0
	v_mfma_f32_16x16x32_bf16 v[14:17], v[146:149], v[178:181], 0
	v_mfma_f32_16x16x32_bf16 v[10:13], v[154:157], v[178:181], 0
	v_mfma_f32_16x16x32_bf16 v[6:9], v[146:149], v[186:189], 0
	v_mfma_f32_16x16x32_bf16 v[2:5], v[154:157], v[186:189], 0
	v_mfma_f32_16x16x32_bf16 v[30:33], v[150:153], v[166:169], v[30:33]
	v_mfma_f32_16x16x32_bf16 v[26:29], v[158:161], v[166:169], v[26:29]
	v_mfma_f32_16x16x32_bf16 v[22:25], v[150:153], v[174:177], v[22:25]
	v_mfma_f32_16x16x32_bf16 v[18:21], v[158:161], v[174:177], v[18:21]
	v_mfma_f32_16x16x32_bf16 v[14:17], v[150:153], v[182:185], v[14:17]
	v_mfma_f32_16x16x32_bf16 v[10:13], v[158:161], v[182:185], v[10:13]
	v_mfma_f32_16x16x32_bf16 v[6:9], v[150:153], v[190:193], v[6:9]
	v_mfma_f32_16x16x32_bf16 v[2:5], v[158:161], v[190:193], v[2:5]
	s_setprio 0
	s_barrier
	s_add_i32 s18, 0, 0x18000
	v_add_u32_e32 v1, s18, v218
	s_add_i32 s35, 0, 0x1c000
	ds_read_b128 v[130:133], v1
	ds_read_b128 v[134:137], v1 offset:1024
	ds_read_b128 v[138:141], v1 offset:2048
	ds_read_b128 v[142:145], v1 offset:3072
	v_add_u32_e32 v1, s35, v218
	ds_read_b128 v[146:149], v1
	ds_read_b128 v[150:153], v1 offset:1024
	ds_read_b128 v[154:157], v1 offset:2048
	ds_read_b128 v[158:161], v1 offset:3072
	s_add_u32 s46, s46, s70
	s_addc_u32 s47, s47, 0
	s_mov_b32 m0, s93
	v_lshl_add_u64 v[226:227], s[46:47], 0, v[194:195]
	ds_read_b128 v[162:165], v219 offset:32768
	ds_read_b128 v[166:169], v219 offset:33792
	ds_read_b128 v[170:173], v219 offset:34816
	ds_read_b128 v[174:177], v219 offset:35840
	ds_read_b128 v[178:181], v219 offset:36864
	ds_read_b128 v[182:185], v219 offset:37888
	ds_read_b128 v[186:189], v219 offset:38912
	ds_read_b128 v[190:193], v219 offset:39936
	global_load_lds_dwordx4 v[226:227], off
	v_lshl_add_u64 v[226:227], s[46:47], 0, v[204:205]
	s_mov_b32 m0, s3
	s_nop 0
	global_load_lds_dwordx4 v[226:227], off
	s_waitcnt vmcnt(8)
	s_waitcnt lgkmcnt(0)
	s_barrier
	s_setprio 1
	s_waitcnt lgkmcnt(0)
	v_mfma_f32_16x16x32_bf16 v[126:129], v[130:133], v[162:165], v[126:129]
	v_mfma_f32_16x16x32_bf16 v[122:125], v[138:141], v[162:165], v[122:125]
	v_mfma_f32_16x16x32_bf16 v[118:121], v[130:133], v[170:173], v[118:121]
	v_mfma_f32_16x16x32_bf16 v[114:117], v[138:141], v[170:173], v[114:117]
	v_mfma_f32_16x16x32_bf16 v[110:113], v[130:133], v[178:181], v[110:113]
	v_mfma_f32_16x16x32_bf16 v[106:109], v[138:141], v[178:181], v[106:109]
	v_mfma_f32_16x16x32_bf16 v[102:105], v[130:133], v[186:189], v[102:105]
	v_mfma_f32_16x16x32_bf16 v[98:101], v[138:141], v[186:189], v[98:101]
	v_mfma_f32_16x16x32_bf16 v[126:129], v[134:137], v[166:169], v[126:129]
	v_mfma_f32_16x16x32_bf16 v[122:125], v[142:145], v[166:169], v[122:125]
	v_mfma_f32_16x16x32_bf16 v[118:121], v[134:137], v[174:177], v[118:121]
	v_mfma_f32_16x16x32_bf16 v[114:117], v[142:145], v[174:177], v[114:117]
	v_mfma_f32_16x16x32_bf16 v[110:113], v[134:137], v[182:185], v[110:113]
	v_mfma_f32_16x16x32_bf16 v[106:109], v[142:145], v[182:185], v[106:109]
	v_mfma_f32_16x16x32_bf16 v[102:105], v[134:137], v[190:193], v[102:105]
	v_mfma_f32_16x16x32_bf16 v[98:101], v[142:145], v[190:193], v[98:101]
	s_setprio 0
	s_setprio 1
	v_mfma_f32_16x16x32_bf16 v[94:97], v[146:149], v[162:165], v[94:97]
	v_mfma_f32_16x16x32_bf16 v[90:93], v[154:157], v[162:165], v[90:93]
	v_mfma_f32_16x16x32_bf16 v[86:89], v[146:149], v[170:173], v[86:89]
	v_mfma_f32_16x16x32_bf16 v[82:85], v[154:157], v[170:173], v[82:85]
	v_mfma_f32_16x16x32_bf16 v[78:81], v[146:149], v[178:181], v[78:81]
	v_mfma_f32_16x16x32_bf16 v[74:77], v[154:157], v[178:181], v[74:77]
	v_mfma_f32_16x16x32_bf16 v[70:73], v[146:149], v[186:189], v[70:73]
	v_mfma_f32_16x16x32_bf16 v[66:69], v[154:157], v[186:189], v[66:69]
	v_mfma_f32_16x16x32_bf16 v[94:97], v[150:153], v[166:169], v[94:97]
	v_mfma_f32_16x16x32_bf16 v[90:93], v[158:161], v[166:169], v[90:93]
	v_mfma_f32_16x16x32_bf16 v[86:89], v[150:153], v[174:177], v[86:89]
	v_mfma_f32_16x16x32_bf16 v[82:85], v[158:161], v[174:177], v[82:85]
	v_mfma_f32_16x16x32_bf16 v[78:81], v[150:153], v[182:185], v[78:81]
	v_mfma_f32_16x16x32_bf16 v[74:77], v[158:161], v[182:185], v[74:77]
	v_mfma_f32_16x16x32_bf16 v[70:73], v[150:153], v[190:193], v[70:73]
	v_mfma_f32_16x16x32_bf16 v[66:69], v[158:161], v[190:193], v[66:69]
	s_setprio 0
	s_barrier
; #define PG8_STAGE(bufoff, gbase, voff) do { _Pragma("unroll") for (int _i = 0; _i < 2; ++_i) \
;         __builtin_amdgcn_global_load_lds((const unsigned*)((const char*)(gbase) + (voff)[_i]), (PG8_LAS unsigned*)(lds + (bufoff) + ldsw + _i * 8192), 16, 0, 0); } while (0)
; #define PG8_LDA(dst, b, h) do { _Pragma("unroll") for (int m = 0; m < 4; ++m) _Pragma("unroll") for (int k = 0; k < 2; ++k) dst[m][k] = *(const PG8_LAS bf16x8*)(lds + PG8_SA(b, h) + aoff + m * 2048 + k * 1024); } while (0)
; #define PG8_MMA(ai, bj, At, Bt) do { __builtin_amdgcn_s_setprio(1); _Pragma("unroll") for (int m = 0; m < 4; ++m) _Pragma("unroll") for (int n = 0; n < 2; ++n) _Pragma("unroll") for (int k = 0; k < 2; ++k) \
;         acc[ai][bj][m][n] = __builtin_amdgcn_mfma_f32_16x16x32_bf16(Bt[n][k], At[m][k], acc[ai][bj][m][n], 0, 0, 0); __builtin_amdgcn_s_setprio(0); } while (0)
; #define PG8_WAIT_V(n) asm volatile("s_waitcnt vmcnt(" #n ")" ::: "memory")
; #define PG8_WAIT_L(n) asm volatile("s_waitcnt lgkmcnt(" #n ")" ::: "memory")
; #define PG8_BAR __builtin_amdgcn_s_barrier()
; #define PG8_SCHED __builtin_amdgcn_sched_barrier(0)
; template <class Epi, class Sched>
; __device__ __forceinline__ void gemm_phase(PG8_LAS unsigned char* lds, const Gemm g, const Sched& S, const Epi& E) {
;     ...
;             PG8_LDA(At, 1, 1); PG8_STAGE(PG8_SB(1, 0), b3, voffB); PG8_STAGE(PG8_SB(1, 1), b3 + hstep, voffB); PG8_STAGE(PG8_SA(1, 0), a3, voffA);
;             PG8_WAIT_V(8); PG8_WAIT_L(0); PG8_BAR; PG8_MMA(1, 0, At, B0); PG8_MMA(1, 1, At, B1); PG8_BAR; PG8_SCHED;
;         }
	s_add_i32 s18, s18, s25
	v_lshl_add_u64 v[212:213], v[212:213], 0, s[0:1]
	s_mov_b32 m0, s18
	ds_read_b128 v[162:165], v219 offset:49152
	ds_read_b128 v[166:169], v219 offset:50176
	ds_read_b128 v[170:173], v219 offset:51200
	ds_read_b128 v[174:177], v219 offset:52224
	ds_read_b128 v[178:181], v219 offset:53248
	ds_read_b128 v[182:185], v219 offset:54272
	ds_read_b128 v[186:189], v219 offset:55296
	ds_read_b128 v[190:193], v219 offset:56320
	global_load_lds_dwordx4 v[212:213], off
	v_lshl_add_u64 v[212:213], v[214:215], 0, s[0:1]
	s_add_i32 m0, s18, 0x2000
	s_add_i32 s18, s35, s25
	global_load_lds_dwordx4 v[212:213], off
	v_lshl_add_u64 v[212:213], v[216:217], 0, s[0:1]
	s_mov_b32 m0, s18
	s_nop 0
	global_load_lds_dwordx4 v[212:213], off
	v_lshl_add_u64 v[212:213], v[220:221], 0, s[0:1]
	s_add_i32 m0, s18, 0x2000
	s_nop 0
	global_load_lds_dwordx4 v[212:213], off
	v_lshl_add_u64 v[212:213], v[222:223], 0, s[0:1]
	s_mov_b32 m0, s39
	s_nop 0
	global_load_lds_dwordx4 v[212:213], off
	v_lshl_add_u64 v[212:213], v[224:225], 0, s[0:1]
	s_mov_b32 m0, s4
	s_nop 0
	global_load_lds_dwordx4 v[212:213], off
	s_waitcnt vmcnt(8)
	s_waitcnt lgkmcnt(0)
	s_barrier
	s_setprio 1
	s_waitcnt lgkmcnt(0)
	v_mfma_f32_16x16x32_bf16 v[62:65], v[130:133], v[162:165], v[62:65]
	v_mfma_f32_16x16x32_bf16 v[58:61], v[138:141], v[162:165], v[58:61]
	v_mfma_f32_16x16x32_bf16 v[54:57], v[130:133], v[170:173], v[54:57]
	v_mfma_f32_16x16x32_bf16 v[50:53], v[138:141], v[170:173], v[50:53]
	v_mfma_f32_16x16x32_bf16 v[46:49], v[130:133], v[178:181], v[46:49]
	v_mfma_f32_16x16x32_bf16 v[42:45], v[138:141], v[178:181], v[42:45]
	v_mfma_f32_16x16x32_bf16 v[38:41], v[130:133], v[186:189], v[38:41]
	v_mfma_f32_16x16x32_bf16 v[34:37], v[138:141], v[186:189], v[34:37]
	v_mfma_f32_16x16x32_bf16 v[62:65], v[134:137], v[166:169], v[62:65]
	v_mfma_f32_16x16x32_bf16 v[58:61], v[142:145], v[166:169], v[58:61]
	v_mfma_f32_16x16x32_bf16 v[54:57], v[134:137], v[174:177], v[54:57]
	v_mfma_f32_16x16x32_bf16 v[50:53], v[142:145], v[174:177], v[50:53]
	v_mfma_f32_16x16x32_bf16 v[46:49], v[134:137], v[182:185], v[46:49]
	v_mfma_f32_16x16x32_bf16 v[42:45], v[142:145], v[182:185], v[42:45]
	v_mfma_f32_16x16x32_bf16 v[38:41], v[134:137], v[190:193], v[38:41]
	v_mfma_f32_16x16x32_bf16 v[34:37], v[142:145], v[190:193], v[34:37]
	s_setprio 0
	s_setprio 1
	v_mfma_f32_16x16x32_bf16 v[30:33], v[146:149], v[162:165], v[30:33]
	v_mfma_f32_16x16x32_bf16 v[26:29], v[154:157], v[162:165], v[26:29]
	v_mfma_f32_16x16x32_bf16 v[22:25], v[146:149], v[170:173], v[22:25]
	v_mfma_f32_16x16x32_bf16 v[18:21], v[154:157], v[170:173], v[18:21]
	v_mfma_f32_16x16x32_bf16 v[14:17], v[146:149], v[178:181], v[14:17]
	v_mfma_f32_16x16x32_bf16 v[10:13], v[154:157], v[178:181], v[10:13]
	v_mfma_f32_16x16x32_bf16 v[6:9], v[146:149], v[186:189], v[6:9]
	v_mfma_f32_16x16x32_bf16 v[2:5], v[154:157], v[186:189], v[2:5]
	v_mfma_f32_16x16x32_bf16 v[30:33], v[150:153], v[166:169], v[30:33]
	v_mfma_f32_16x16x32_bf16 v[26:29], v[158:161], v[166:169], v[26:29]
	v_mfma_f32_16x16x32_bf16 v[22:25], v[150:153], v[174:177], v[22:25]
	v_mfma_f32_16x16x32_bf16 v[18:21], v[158:161], v[174:177], v[18:21]
	v_mfma_f32_16x16x32_bf16 v[14:17], v[150:153], v[182:185], v[14:17]
	v_mfma_f32_16x16x32_bf16 v[10:13], v[158:161], v[182:185], v[10:13]
	v_mfma_f32_16x16x32_bf16 v[6:9], v[150:153], v[190:193], v[6:9]
	v_mfma_f32_16x16x32_bf16 v[2:5], v[158:161], v[190:193], v[2:5]
	s_setprio 0
	s_barrier
	s_add_u32 s44, s44, 0x100
	s_addc_u32 s45, s45, 0
	s_add_u32 s14, s14, 0x100
	s_addc_u32 s15, s15, 0
	s_cmp_ge_u32 s34, s2
	s_mov_b32 s18, s34
	.p2align	6
